# stack_forget_nowait_kvhoist_fixup3
# speedup vs baseline: 1.0073x; 1.0024x over previous
.LBB0_880:
	s_or_b64 exec, exec, s[2:3]
	s_mov_b64 s[8:9], s[84:85]
	v_mov_b32_e32 v0, v165
	v_readlane_b32 s2, v253, 3
	s_waitcnt lgkmcnt(0)
	s_barrier
	s_nop 0
	v_add_u32_e32 v64, s2, v0
	s_mov_b32 s2, 0x1ff80
	v_cmp_gt_i32_e32 vcc, s2, v64
	s_and_saveexec_b64 s[2:3], vcc
	s_cbranch_execz .LBB0_897
	s_load_dwordx2 s[10:11], s[8:9], 0x90
	s_load_dwordx4 s[4:7], s[8:9], 0x68
	v_lshlrev_b32_e32 v65, 2, v64
	s_mov_b64 s[26:27], 0
	s_waitcnt lgkmcnt(0)
	s_add_u32 s8, s10, 0x8500000
	s_addc_u32 s9, s11, 0
	s_add_u32 s10, s10, 0xb100000
	s_addc_u32 s11, s11, 0
	s_add_u32 s12, s4, s48
	s_addc_u32 s13, s5, 0
	s_add_u32 s6, s6, s33
	s_addc_u32 s7, s7, 0
	s_add_u32 s14, s12, 0x5800
	s_addc_u32 s15, s13, 0
	s_add_u32 s16, s12, 0xb000
	s_addc_u32 s17, s13, 0
	s_add_u32 s18, s6, 0x2c00
	s_addc_u32 s19, s7, 0
	s_add_u32 s20, s12, 0x2c00
	s_addc_u32 s21, s13, 0
	s_add_u32 s22, s12, 0x8400
	s_addc_u32 s23, s13, 0
	s_add_u32 s24, s12, 0xdc00
	s_addc_u32 s25, s13, 0
	s_lshl_b32 s33, s94, 2
	s_branch .LBB0_883
.LBB0_883:
	s_mov_b32 s4, 0x2e8ba2e9
	v_mul_hi_i32 v0, v64, s4
	v_ashrrev_i32_e32 v2, 7, v0
	v_lshrrev_b32_e32 v3, 31, v0
	v_add_u32_e32 v66, v2, v3
	v_mul_i32_i24_e32 v2, 0x2c0, v66
	v_lshlrev_b32_e32 v2, 2, v2
	v_sub_u32_e32 v60, v65, v2
	v_ashrrev_i32_e32 v61, 31, v60
	v_lshlrev_b64 v[94:95], 2, v[60:61]
	v_lshl_add_u64 v[96:97], s[6:7], 0, v[94:95]
	v_lshl_add_u64 v[98:99], s[18:19], 0, v[94:95]
	global_load_dwordx4 v[40:43], v[96:97], off
	global_load_dwordx4 v[44:47], v[98:99], off
	v_lshl_add_u64 v[96:97], s[12:13], 0, v[94:95]
	v_lshl_add_u64 v[98:99], s[20:21], 0, v[94:95]
	global_load_dwordx4 v[48:51], v[96:97], off
	global_load_dwordx4 v[52:55], v[98:99], off
	v_lshl_add_u64 v[96:97], s[14:15], 0, v[94:95]
	v_lshl_add_u64 v[98:99], s[22:23], 0, v[94:95]
	global_load_dwordx4 v[56:59], v[96:97], off
	global_load_dwordx4 v[68:71], v[98:99], off
	v_lshl_add_u64 v[96:97], s[16:17], 0, v[94:95]
	v_lshl_add_u64 v[98:99], s[24:25], 0, v[94:95]
	global_load_dwordx4 v[72:75], v[96:97], off
	global_load_dwordx4 v[76:79], v[98:99], off
.Lfx_loop:
	v_and_b32_e32 v0, 31, v66
	v_cmp_ne_u32_e64 s[4:5], 0, v0
	v_add_u32_e32 v0, -1, v66
	v_mul_hi_i32_i24_e32 v3, 0x16000, v66
	v_mul_i32_i24_e32 v2, 0x16000, v66
	v_mul_hi_i32_i24_e32 v5, 0x16000, v0
	v_mul_i32_i24_e32 v4, 0x16000, v0
	v_lshl_add_u64 v[2:3], s[8:9], 0, v[2:3]
	v_lshl_add_u64 v[24:25], s[8:9], 0, v[4:5]
	v_lshl_add_u64 v[2:3], v[60:61], 2, v[2:3]
	v_lshl_add_u64 v[24:25], v[60:61], 2, v[24:25]
	s_mov_b64 s[28:29], 0x2c00
	s_mov_b64 s[30:31], 0xb000
	v_lshl_add_u64 v[80:81], s[28:29], 0, v[2:3]
	v_lshl_add_u64 v[86:87], s[30:31], 0, v[24:25]
	global_load_dwordx4 v[4:7], v[2:3], off
	v_lshl_add_u64 v[82:83], s[28:29], 0, v[80:81]
	global_load_dwordx4 v[8:11], v[80:81], off
	v_lshl_add_u64 v[88:89], s[28:29], 0, v[86:87]
	global_load_dwordx4 v[20:23], v[86:87], off
	v_lshl_add_u64 v[84:85], s[28:29], 0, v[82:83]
	global_load_dwordx4 v[12:15], v[82:83], off
	v_lshl_add_u64 v[90:91], s[28:29], 0, v[88:89]
	global_load_dwordx4 v[28:31], v[88:89], off
	global_load_dwordx4 v[16:19], v[84:85], off
	v_lshl_add_u64 v[92:93], s[28:29], 0, v[90:91]
	global_load_dwordx4 v[32:35], v[90:91], off
	global_load_dwordx4 v[36:39], v[92:93], off
	s_waitcnt vmcnt(0)
	v_cndmask_b32_e64 v20, 0, v20, s[4:5]
	v_cndmask_b32_e64 v21, 0, v21, s[4:5]
	v_cndmask_b32_e64 v22, 0, v22, s[4:5]
	v_cndmask_b32_e64 v23, 0, v23, s[4:5]
	v_cndmask_b32_e64 v28, 0, v28, s[4:5]
	v_cndmask_b32_e64 v29, 0, v29, s[4:5]
	v_cndmask_b32_e64 v30, 0, v30, s[4:5]
	v_cndmask_b32_e64 v31, 0, v31, s[4:5]
	v_cndmask_b32_e64 v32, 0, v32, s[4:5]
	v_cndmask_b32_e64 v33, 0, v33, s[4:5]
	v_cndmask_b32_e64 v34, 0, v34, s[4:5]
	v_cndmask_b32_e64 v35, 0, v35, s[4:5]
	v_cndmask_b32_e64 v36, 0, v36, s[4:5]
	v_cndmask_b32_e64 v37, 0, v37, s[4:5]
	v_cndmask_b32_e64 v38, 0, v38, s[4:5]
	v_cndmask_b32_e64 v39, 0, v39, s[4:5]
	v_fma_f32 v80, v48, v20, v40
	v_fma_f32 v84, v52, v28, v44
	v_fma_f32 v88, v48, v32, v40
	v_fma_f32 v92, v52, v36, v44
	v_fma_f32 v81, v49, v21, v41
	v_fma_f32 v85, v53, v29, v45
	v_fma_f32 v89, v49, v33, v41
	v_fma_f32 v93, v53, v37, v45
	v_fma_f32 v82, v50, v22, v42
	v_fma_f32 v86, v54, v30, v46
	v_fma_f32 v90, v50, v34, v42
	v_fma_f32 v94, v54, v38, v46
	v_fma_f32 v83, v51, v23, v43
	v_fma_f32 v87, v55, v31, v47
	v_fma_f32 v91, v51, v35, v43
	v_fma_f32 v95, v55, v39, v47
	v_fma_f32 v80, v56, v32, v80
	v_fma_f32 v84, v68, v36, v84
	v_fma_f32 v88, v56, v4, v88
	v_fma_f32 v92, v68, v8, v92
	v_fma_f32 v81, v57, v33, v81
	v_fma_f32 v85, v69, v37, v85
	v_fma_f32 v89, v57, v5, v89
	v_fma_f32 v93, v69, v9, v93
	v_fma_f32 v82, v58, v34, v82
	v_fma_f32 v86, v70, v38, v86
	v_fma_f32 v90, v58, v6, v90
	v_fma_f32 v94, v70, v10, v94
	v_fma_f32 v83, v59, v35, v83
	v_fma_f32 v87, v71, v39, v87
	v_fma_f32 v91, v59, v7, v91
	v_fma_f32 v95, v71, v11, v95
	v_fma_f32 v80, v72, v4, v80
	v_fma_f32 v84, v76, v8, v84
	v_fma_f32 v88, v72, v12, v88
	v_fma_f32 v92, v76, v16, v92
	v_fma_f32 v81, v73, v5, v81
	v_fma_f32 v85, v77, v9, v85
	v_fma_f32 v89, v73, v13, v89
	v_fma_f32 v93, v77, v17, v93
	v_fma_f32 v82, v74, v6, v82
	v_fma_f32 v86, v78, v10, v86
	v_fma_f32 v90, v74, v14, v90
	v_fma_f32 v94, v78, v18, v94
	v_fma_f32 v83, v75, v7, v83
	v_fma_f32 v87, v79, v11, v87
	v_fma_f32 v91, v75, v15, v91
	v_fma_f32 v95, v79, v19, v95
	v_mul_f32_e32 v20, 0xbfb8aa3b, v80
	v_mul_f32_e32 v21, 0xbfb8aa3b, v81
	v_mul_f32_e32 v22, 0xbfb8aa3b, v82
	v_mul_f32_e32 v23, 0xbfb8aa3b, v83
	v_mul_f32_e32 v28, 0xbfb8aa3b, v88
	v_mul_f32_e32 v29, 0xbfb8aa3b, v89
	v_mul_f32_e32 v30, 0xbfb8aa3b, v90
	v_mul_f32_e32 v31, 0xbfb8aa3b, v91
	v_exp_f32_e32 v20, v20
	v_exp_f32_e32 v21, v21
	v_exp_f32_e32 v22, v22
	v_exp_f32_e32 v23, v23
	v_exp_f32_e32 v28, v28
	v_exp_f32_e32 v29, v29
	v_exp_f32_e32 v30, v30
	v_exp_f32_e32 v31, v31
	v_add_f32_e32 v20, 1.0, v20
	v_add_f32_e32 v21, 1.0, v21
	v_add_f32_e32 v22, 1.0, v22
	v_add_f32_e32 v23, 1.0, v23
	v_add_f32_e32 v28, 1.0, v28
	v_add_f32_e32 v29, 1.0, v29
	v_add_f32_e32 v30, 1.0, v30
	v_add_f32_e32 v31, 1.0, v31
	v_rcp_f32_e32 v20, v20
	v_rcp_f32_e32 v21, v21
	v_rcp_f32_e32 v22, v22
	v_rcp_f32_e32 v23, v23
	v_rcp_f32_e32 v28, v28
	v_rcp_f32_e32 v29, v29
	v_rcp_f32_e32 v30, v30
	v_rcp_f32_e32 v31, v31
	v_mul_f32_e32 v20, v80, v20
	v_mul_f32_e32 v21, v81, v21
	v_mul_f32_e32 v22, v82, v22
	v_mul_f32_e32 v23, v83, v23
	v_mul_f32_e32 v28, v88, v28
	v_mul_f32_e32 v29, v89, v29
	v_mul_f32_e32 v30, v90, v30
	v_mul_f32_e32 v31, v91, v31
	v_mul_f32_e32 v20, v84, v20
	v_mul_f32_e32 v21, v85, v21
	v_mul_f32_e32 v22, v86, v22
	v_mul_f32_e32 v23, v87, v23
	v_mul_f32_e32 v28, v92, v28
	v_mul_f32_e32 v29, v93, v29
	v_mul_f32_e32 v30, v94, v30
	v_mul_f32_e32 v31, v95, v31
	v_cvt_pk_bf16_f32 v2, v20, v21
	v_cvt_pk_bf16_f32 v3, v22, v23
	v_cvt_pk_bf16_f32 v6, v28, v29
	v_cvt_pk_bf16_f32 v7, v30, v31
	v_lshlrev_b32_e32 v0, 6, v66
	s_movk_i32 s4, 0x1600
	v_mov_b64_e32 v[4:5], s[10:11]
	v_mad_i64_i32 v[4:5], s[4:5], v0, s4, v[4:5]
	s_mov_b64 s[28:29], 0x1600
	v_add_u32_e32 v66, 0xba, v66
	s_movk_i32 s4, 0x1ff
	v_lshl_add_u64 v[4:5], v[60:61], 1, v[4:5]
	v_cmp_lt_i32_e32 vcc, s4, v66
	v_lshl_add_u64 v[8:9], s[28:29], 0, v[4:5]
	s_or_b64 s[26:27], vcc, s[26:27]
	global_store_dwordx2 v[4:5], v[2:3], off
	global_store_dwordx2 v[8:9], v[6:7], off
	s_andn2_b64 exec, exec, s[26:27]
	s_cbranch_execnz .Lfx_loop
